# nt_hint_on_phase0_x_row_loads
# speedup vs baseline: 1.0115x; 1.0044x over previous
.LBB0_131:
	s_add_i32 s8, s34, s86
	s_cmp_lt_i32 s8, 0x10000
	s_cselect_b32 s0, s8, s34
	s_ashr_i32 s35, s34, 31
	s_ashr_i32 s1, s0, 31
	s_lshl_b64 s[4:5], s[34:35], 12
	v_lshl_add_u64 v[24:25], v[6:7], 0, s[4:5]
	s_lshl_b64 s[4:5], s[0:1], 12
	global_load_dwordx4 v[12:15], v[24:25], off nt
	global_load_dwordx4 v[16:19], v[24:25], off offset:1024 nt
	global_load_dwordx4 v[20:23], v[24:25], off offset:2048 nt
	s_nop 0
	global_load_dwordx4 v[24:27], v[24:25], off offset:3072 nt
	v_lshl_add_u64 v[40:41], v[6:7], 0, s[4:5]
	global_load_dwordx4 v[28:31], v[40:41], off nt
	global_load_dwordx4 v[32:35], v[40:41], off offset:1024 nt
	global_load_dwordx4 v[36:39], v[40:41], off offset:2048 nt
	s_nop 0
	global_load_dwordx4 v[40:43], v[40:41], off offset:3072 nt
	s_lshl_b64 s[0:1], s[0:1], 11
	v_lshl_add_u64 v[46:47], v[2:3], 0, s[0:1]
	s_lshl_b64 s[12:13], s[34:35], 11
	v_lshl_add_u64 v[44:45], v[2:3], 0, s[12:13]
	s_add_i32 s34, s8, s86
	s_cmp_gt_i32 s34, 0xffff
	s_waitcnt vmcnt(7)
	v_mov_b32_e32 v50, v13
	s_waitcnt vmcnt(6)
	v_mov_b32_e32 v51, v17
	v_mov_b32_e32 v48, v12
	v_mov_b32_e32 v49, v16
	s_waitcnt vmcnt(5)
	v_mov_b32_e32 v58, v21
	s_waitcnt vmcnt(4)
	v_mov_b32_e32 v59, v25
	v_pk_mul_f32 v[50:51], v[50:51], v[50:51]
	s_waitcnt vmcnt(3)
	v_mov_b32_e32 v66, v29
	s_waitcnt vmcnt(2)
	v_mov_b32_e32 v67, v33
	v_mov_b32_e32 v56, v20
	v_mov_b32_e32 v57, v24
	v_mov_b32_e32 v64, v28
	v_mov_b32_e32 v65, v32
	v_pk_mul_f32 v[58:59], v[58:59], v[58:59]
	s_waitcnt vmcnt(1)
	v_mov_b32_e32 v74, v37
	s_waitcnt vmcnt(0)
	v_mov_b32_e32 v75, v41
	v_pk_fma_f32 v[48:49], v[48:49], v[48:49], v[50:51]
	v_pk_mul_f32 v[50:51], v[66:67], v[66:67]
	v_mov_b32_e32 v52, v14
	v_mov_b32_e32 v53, v18
	v_mov_b32_e32 v60, v22
	v_mov_b32_e32 v61, v26
	v_mov_b32_e32 v68, v30
	v_mov_b32_e32 v69, v34
	v_mov_b32_e32 v72, v36
	v_mov_b32_e32 v73, v40
	v_pk_fma_f32 v[56:57], v[56:57], v[56:57], v[58:59]
	v_pk_mul_f32 v[58:59], v[74:75], v[74:75]
	v_pk_fma_f32 v[50:51], v[64:65], v[64:65], v[50:51]
	v_mov_b32_e32 v54, v15
	v_mov_b32_e32 v55, v19
	v_mov_b32_e32 v70, v31
	v_mov_b32_e32 v71, v35
	v_mov_b32_e32 v76, v38
	v_mov_b32_e32 v77, v42
	v_pk_fma_f32 v[48:49], v[52:53], v[52:53], v[48:49]
	v_pk_fma_f32 v[52:53], v[60:61], v[60:61], v[56:57]
	v_pk_fma_f32 v[56:57], v[72:73], v[72:73], v[58:59]
	v_pk_fma_f32 v[50:51], v[68:69], v[68:69], v[50:51]
	v_mov_b32_e32 v62, v23
	v_mov_b32_e32 v63, v27
	v_mov_b32_e32 v78, v39
	v_mov_b32_e32 v79, v43
	v_pk_fma_f32 v[48:49], v[54:55], v[54:55], v[48:49]
	v_pk_fma_f32 v[54:55], v[76:77], v[76:77], v[56:57]
	v_pk_fma_f32 v[50:51], v[70:71], v[70:71], v[50:51]
	v_pk_fma_f32 v[52:53], v[62:63], v[62:63], v[52:53]
	v_pk_fma_f32 v[54:55], v[78:79], v[78:79], v[54:55]
	v_mov_b32_e32 v57, v48
	v_mov_b32_e32 v56, v50
	v_mov_b32_e32 v48, v51
	v_mov_b32_e32 v59, v52
	v_mov_b32_e32 v58, v54
	v_pk_add_f32 v[48:49], v[56:57], v[48:49]
	v_mov_b32_e32 v52, v55
	v_pk_add_f32 v[48:49], v[48:49], v[58:59]
	s_nop 0
	v_pk_add_f32 v[48:49], v[48:49], v[52:53]
	ds_bpermute_b32 v51, v1, v49
	ds_bpermute_b32 v50, v1, v48
	s_waitcnt lgkmcnt(0)
	v_pk_add_f32 v[48:49], v[48:49], v[50:51]
	ds_bpermute_b32 v51, v5, v49
	ds_bpermute_b32 v50, v5, v48
	s_waitcnt lgkmcnt(0)
	v_pk_add_f32 v[48:49], v[48:49], v[50:51]
	ds_bpermute_b32 v51, v8, v49
	ds_bpermute_b32 v50, v8, v48
	s_waitcnt lgkmcnt(0)
	v_pk_add_f32 v[48:49], v[48:49], v[50:51]
	ds_bpermute_b32 v51, v9, v49
	ds_bpermute_b32 v50, v9, v48
	s_waitcnt lgkmcnt(0)
	v_pk_add_f32 v[48:49], v[48:49], v[50:51]
	ds_bpermute_b32 v51, v10, v49
	ds_bpermute_b32 v50, v10, v48
	s_waitcnt lgkmcnt(0)
	v_pk_add_f32 v[48:49], v[48:49], v[50:51]
	ds_bpermute_b32 v51, v11, v49
	ds_bpermute_b32 v50, v11, v48
	s_waitcnt lgkmcnt(0)
	v_pk_add_f32 v[48:49], v[48:49], v[50:51]
	s_nop 0
	v_pk_fma_f32 v[48:49], v[48:49], s[2:3], v[4:5] op_sel_hi:[1,0,0]
	s_nop 0
	v_mul_f32_e32 v50, 0x4b800000, v49
	v_cmp_gt_f32_e64 s[0:1], s3, v49
	v_mul_f32_e32 v51, 0x4b800000, v48
	v_cmp_gt_f32_e32 vcc, s3, v48
	v_cndmask_b32_e64 v49, v49, v50, s[0:1]
	v_rsq_f32_e32 v49, v49
	v_cndmask_b32_e32 v48, v48, v51, vcc
	v_rsq_f32_e32 v48, v48
	v_mul_f32_e32 v50, 0x45800000, v49
	v_cndmask_b32_e64 v49, v49, v50, s[0:1]
	v_mul_f32_e32 v51, 0x45800000, v48
	v_mul_f32_e32 v12, v12, v49
	v_mul_f32_e32 v13, v13, v49
	v_cndmask_b32_e32 v48, v48, v51, vcc
	v_mul_f32_e32 v14, v14, v49
	v_mul_f32_e32 v15, v15, v49
	v_cvt_pk_bf16_f32 v12, v12, v13
	v_cvt_pk_bf16_f32 v13, v14, v15
	v_mul_f32_e32 v28, v28, v48
	v_mul_f32_e32 v29, v29, v48
	v_mul_f32_e32 v30, v30, v48
	v_mul_f32_e32 v31, v31, v48
	global_store_dwordx2 v[44:45], v[12:13], off
	v_cvt_pk_bf16_f32 v12, v28, v29
	v_cvt_pk_bf16_f32 v13, v30, v31
	v_mul_f32_e32 v16, v16, v49
	v_mul_f32_e32 v17, v17, v49
	v_mul_f32_e32 v18, v18, v49
	v_mul_f32_e32 v19, v19, v49
	global_store_dwordx2 v[46:47], v[12:13], off
	v_cvt_pk_bf16_f32 v12, v16, v17
	v_cvt_pk_bf16_f32 v13, v18, v19
	v_mul_f32_e32 v32, v32, v48
	v_mul_f32_e32 v33, v33, v48
	v_mul_f32_e32 v34, v34, v48
	v_mul_f32_e32 v35, v35, v48
	global_store_dwordx2 v[44:45], v[12:13], off offset:512
	v_cvt_pk_bf16_f32 v12, v32, v33
	v_cvt_pk_bf16_f32 v13, v34, v35
	v_mul_f32_e32 v20, v20, v49
	v_mul_f32_e32 v21, v21, v49
	v_mul_f32_e32 v22, v22, v49
	v_mul_f32_e32 v23, v23, v49
	global_store_dwordx2 v[46:47], v[12:13], off offset:512
	v_cvt_pk_bf16_f32 v12, v20, v21
	v_cvt_pk_bf16_f32 v13, v22, v23
	v_mul_f32_e32 v36, v36, v48
	v_mul_f32_e32 v37, v37, v48
	v_mul_f32_e32 v38, v38, v48
	v_mul_f32_e32 v39, v39, v48
	global_store_dwordx2 v[44:45], v[12:13], off offset:1024
	v_cvt_pk_bf16_f32 v12, v36, v37
	v_cvt_pk_bf16_f32 v13, v38, v39
	v_mul_f32_e32 v24, v24, v49
	v_mul_f32_e32 v25, v25, v49
	v_mul_f32_e32 v26, v26, v49
	v_mul_f32_e32 v27, v27, v49
	global_store_dwordx2 v[46:47], v[12:13], off offset:1024
	v_cvt_pk_bf16_f32 v12, v24, v25
	v_cvt_pk_bf16_f32 v13, v26, v27
	v_mul_f32_e32 v40, v40, v48
	v_mul_f32_e32 v41, v41, v48
	v_mul_f32_e32 v42, v42, v48
	v_mul_f32_e32 v43, v43, v48
	global_store_dwordx2 v[44:45], v[12:13], off offset:1536
	v_cvt_pk_bf16_f32 v12, v40, v41
	v_cvt_pk_bf16_f32 v13, v42, v43
	global_store_dwordx2 v[46:47], v[12:13], off offset:1536
	s_cbranch_scc0 .LBB0_131
